# combo8 plus removal of compiler-inserted full vmcnt drains before the first K-loop of five GEMM phases
# speedup vs baseline: 1.0136x; 1.0045x over previous
.LBB0_748:
	v_lshl_add_u64 v[8:9], s[60:61], 0, v[178:179]
	v_mov_b32_e32 v131, v179
	v_and_b32_e32 v167, 15, v166
	v_and_b32_e32 v144, 48, v166
	v_lshlrev_b32_e32 v17, 2, v166
	v_lshl_add_u64 v[10:11], s[60:61], 0, v[130:131]
	v_mov_b32_e32 v135, v179
	s_and_b32 s95, s9, 3
	s_lshl_b32 s0, s10, 13
	v_lshl_or_b32 v16, v167, 6, v144
	v_and_b32_e32 v17, 32, v17
	s_add_i32 m0, s33, 0x18000
	v_lshl_add_u64 v[8:9], v[8:9], 0, s[90:91]
	v_lshl_add_u64 v[12:13], s[34:35], 0, v[134:135]
	v_mov_b32_e32 v133, v179
	s_lshl_b32 s29, s10, 6
	v_bitop3_b32 v18, v16, s0, v17 bitop3:0xde
	s_lshl_b32 s0, s95, 12
	s_waitcnt vmcnt(2)
	s_barrier
	global_load_lds_dwordx4 v[8:9], off
	v_lshl_add_u64 v[8:9], v[10:11], 0, s[90:91]
	s_add_i32 m0, s33, 0x1a000
	s_add_i32 s41, s33, 0x8000
	s_add_i32 s42, s33, 0xa000
	v_lshl_add_u64 v[14:15], s[34:35], 0, v[132:133]
	v_bitop3_b32 v145, v16, s0, v17 bitop3:0xde
	global_load_lds_dwordx4 v[8:9], off
	v_lshl_add_u64 v[8:9], v[12:13], 0, s[90:91]
	s_mov_b32 m0, s41
	s_add_u32 s0, s60, 0x40080
	global_load_lds_dwordx4 v[8:9], off
	v_lshl_add_u64 v[8:9], v[14:15], 0, s[90:91]
	s_mov_b32 m0, s42
	s_addc_u32 s1, s61, 0
	global_load_lds_dwordx4 v[8:9], off
	s_add_i32 m0, s33, 0x1c000
	v_lshl_add_u64 v[8:9], s[0:1], 0, v[178:179]
	global_load_lds_dwordx4 v[8:9], off
	v_lshl_add_u64 v[8:9], s[0:1], 0, v[130:131]
	s_add_i32 m0, s33, 0x1e000
	v_readlane_b32 s0, v254, 56
	global_load_lds_dwordx4 v[8:9], off
	v_lshlrev_b32_e32 v8, 14, v6
	v_and_b32_e32 v8, 0xffff8000, v8
	v_lshl_add_u32 v5, v5, 11, v8
	v_and_b32_e32 v6, 1, v6
	v_lshl_or_b32 v5, v6, 6, v5
	v_lshl_add_u32 v136, v7, 1, v5
	v_lshlrev_b32_e32 v5, 14, v2
	v_and_b32_e32 v5, 0xffff8000, v5
	v_lshl_add_u32 v3, v3, 11, v5
	v_and_b32_e32 v2, 1, v2
	s_waitcnt vmcnt(6)
	v_lshl_or_b32 v2, v2, 6, v3
	v_lshl_add_u32 v138, v4, 1, v2
	v_mov_b32_e32 v2, 0
	s_mov_b32 s8, s0
	v_readlane_b32 s0, v254, 52
	v_or_b32_e32 v168, s29, v167
	v_mov_b32_e32 v137, v179
	v_mov_b32_e32 v139, v179
	s_mov_b32 s43, 0
	v_add_u32_e32 v146, 0, v18
	s_mov_b32 s11, s0
	v_mov_b32_e32 v3, v2
	v_mov_b32_e32 v4, v2
	v_mov_b32_e32 v5, v2
	v_mov_b32_e32 v6, v2
	v_mov_b32_e32 v7, v2
	v_mov_b32_e32 v8, v2
	v_mov_b32_e32 v9, v2
	v_mov_b32_e32 v50, v2
	v_mov_b32_e32 v51, v2
	v_mov_b32_e32 v52, v2
	v_mov_b32_e32 v53, v2
	v_mov_b32_e32 v54, v2
	v_mov_b32_e32 v55, v2
	v_mov_b32_e32 v56, v2
	v_mov_b32_e32 v57, v2
	v_mov_b32_e32 v98, v2
	v_mov_b32_e32 v99, v2
	v_mov_b32_e32 v100, v2
	v_mov_b32_e32 v101, v2
	v_mov_b32_e32 v102, v2
	v_mov_b32_e32 v103, v2
	v_mov_b32_e32 v104, v2
	v_mov_b32_e32 v105, v2
	v_mov_b32_e32 v122, v2
	v_mov_b32_e32 v123, v2
	v_mov_b32_e32 v124, v2
	v_mov_b32_e32 v125, v2
	v_mov_b32_e32 v126, v2
	v_mov_b32_e32 v127, v2
	v_mov_b32_e32 v128, v2
	v_mov_b32_e32 v129, v2
	v_mov_b32_e32 v26, v2
	v_mov_b32_e32 v27, v2
	v_mov_b32_e32 v28, v2
	v_mov_b32_e32 v29, v2
	v_mov_b32_e32 v30, v2
	v_mov_b32_e32 v31, v2
	v_mov_b32_e32 v32, v2
	v_mov_b32_e32 v33, v2
	v_mov_b32_e32 v74, v2
	v_mov_b32_e32 v75, v2
	v_mov_b32_e32 v76, v2
	v_mov_b32_e32 v77, v2
	v_mov_b32_e32 v78, v2
	v_mov_b32_e32 v79, v2
	v_mov_b32_e32 v80, v2
	v_mov_b32_e32 v81, v2
	v_mov_b32_e32 v106, v2
	v_mov_b32_e32 v107, v2
	v_mov_b32_e32 v108, v2
	v_mov_b32_e32 v109, v2
	v_mov_b32_e32 v110, v2
	v_mov_b32_e32 v111, v2
	v_mov_b32_e32 v112, v2
	v_mov_b32_e32 v113, v2
	v_mov_b32_e32 v114, v2
	v_mov_b32_e32 v115, v2
	v_mov_b32_e32 v116, v2
	v_mov_b32_e32 v117, v2
	v_mov_b32_e32 v118, v2
	v_mov_b32_e32 v119, v2
	v_mov_b32_e32 v120, v2
	v_mov_b32_e32 v121, v2
	v_mov_b32_e32 v90, v2
	v_mov_b32_e32 v91, v2
	v_mov_b32_e32 v92, v2
	v_mov_b32_e32 v93, v2
	v_mov_b32_e32 v94, v2
	v_mov_b32_e32 v95, v2
	v_mov_b32_e32 v96, v2
	v_mov_b32_e32 v97, v2
	v_mov_b32_e32 v66, v2
	v_mov_b32_e32 v67, v2
	v_mov_b32_e32 v68, v2
	v_mov_b32_e32 v69, v2
	v_mov_b32_e32 v70, v2
	v_mov_b32_e32 v71, v2
	v_mov_b32_e32 v72, v2
	v_mov_b32_e32 v73, v2
	v_mov_b32_e32 v42, v2
	v_mov_b32_e32 v43, v2
	v_mov_b32_e32 v44, v2
	v_mov_b32_e32 v45, v2
	v_mov_b32_e32 v46, v2
	v_mov_b32_e32 v47, v2
	v_mov_b32_e32 v48, v2
	v_mov_b32_e32 v49, v2
	v_mov_b32_e32 v18, v2
	v_mov_b32_e32 v19, v2
	v_mov_b32_e32 v20, v2
	v_mov_b32_e32 v21, v2
	v_mov_b32_e32 v22, v2
	v_mov_b32_e32 v23, v2
	v_mov_b32_e32 v24, v2
	v_mov_b32_e32 v25, v2
	v_mov_b32_e32 v82, v2
	v_mov_b32_e32 v83, v2
	v_mov_b32_e32 v84, v2
	v_mov_b32_e32 v85, v2
	v_mov_b32_e32 v86, v2
	v_mov_b32_e32 v87, v2
	v_mov_b32_e32 v88, v2
	v_mov_b32_e32 v89, v2
	v_mov_b32_e32 v58, v2
	v_mov_b32_e32 v59, v2
	v_mov_b32_e32 v60, v2
	v_mov_b32_e32 v61, v2
	v_mov_b32_e32 v62, v2
	v_mov_b32_e32 v63, v2
	v_mov_b32_e32 v64, v2
	v_mov_b32_e32 v65, v2
	v_mov_b32_e32 v34, v2
	v_mov_b32_e32 v35, v2
	v_mov_b32_e32 v36, v2
	v_mov_b32_e32 v37, v2
	v_mov_b32_e32 v38, v2
	v_mov_b32_e32 v39, v2
	v_mov_b32_e32 v40, v2
	v_mov_b32_e32 v41, v2
	v_mov_b32_e32 v10, v2
	v_mov_b32_e32 v11, v2
	v_mov_b32_e32 v12, v2
	v_mov_b32_e32 v13, v2
	v_mov_b32_e32 v14, v2
	v_mov_b32_e32 v15, v2
	v_mov_b32_e32 v16, v2
	v_mov_b32_e32 v17, v2
	s_barrier
	v_readlane_b32 s1, v254, 53

.LBB0_810:
	v_lshl_add_u64 v[8:9], s[60:61], 0, v[178:179]
	v_mov_b32_e32 v131, v179
	v_and_b32_e32 v171, 15, v170
	v_and_b32_e32 v169, 48, v170
	v_lshlrev_b32_e32 v17, 2, v170
	v_lshl_add_u64 v[10:11], s[60:61], 0, v[130:131]
	v_mov_b32_e32 v135, v179
	s_and_b32 s10, s9, 3
	s_lshl_b32 s0, s13, 13
	v_lshl_or_b32 v16, v171, 6, v169
	v_and_b32_e32 v17, 32, v17
	s_add_i32 m0, s28, 0x18000
	v_lshl_add_u64 v[8:9], v[8:9], 0, s[90:91]
	v_lshl_add_u64 v[12:13], s[88:89], 0, v[134:135]
	v_mov_b32_e32 v133, v179
	s_lshl_b32 s41, s13, 6
	v_bitop3_b32 v18, v16, s0, v17 bitop3:0xde
	s_lshl_b32 s0, s10, 12
	s_waitcnt vmcnt(2)
	s_barrier
	global_load_lds_dwordx4 v[8:9], off
	v_lshl_add_u64 v[8:9], v[10:11], 0, s[90:91]
	s_add_i32 m0, s28, 0x1a000
	s_add_i32 s85, s28, 0x8000
	s_add_i32 s42, s28, 0xa000
	v_lshl_add_u64 v[14:15], s[88:89], 0, v[132:133]
	v_bitop3_b32 v144, v16, s0, v17 bitop3:0xde
	global_load_lds_dwordx4 v[8:9], off
	v_lshl_add_u64 v[8:9], v[12:13], 0, s[90:91]
	s_mov_b32 m0, s85
	s_add_u32 s0, s60, 0x40080
	global_load_lds_dwordx4 v[8:9], off
	v_lshl_add_u64 v[8:9], v[14:15], 0, s[90:91]
	s_mov_b32 m0, s42
	s_addc_u32 s1, s61, 0
	global_load_lds_dwordx4 v[8:9], off
	s_add_i32 m0, s28, 0x1c000
	v_lshl_add_u64 v[8:9], s[0:1], 0, v[178:179]
	global_load_lds_dwordx4 v[8:9], off
	v_lshl_add_u64 v[8:9], s[0:1], 0, v[130:131]
	s_add_i32 m0, s28, 0x1e000
	v_readlane_b32 s0, v254, 56
	global_load_lds_dwordx4 v[8:9], off
	v_lshlrev_b32_e32 v8, 14, v6
	v_and_b32_e32 v8, 0xffff8000, v8
	v_lshl_add_u32 v5, v5, 11, v8
	v_and_b32_e32 v6, 1, v6
	v_lshl_or_b32 v5, v6, 6, v5
	v_lshl_add_u32 v136, v7, 1, v5
	v_lshlrev_b32_e32 v5, 14, v2
	v_and_b32_e32 v5, 0xffff8000, v5
	v_lshl_add_u32 v3, v3, 11, v5
	v_and_b32_e32 v2, 1, v2
	s_waitcnt vmcnt(6)
	v_lshl_or_b32 v2, v2, 6, v3
	v_lshl_add_u32 v138, v4, 1, v2
	v_mov_b32_e32 v2, 0
	s_mov_b32 s8, s0
	v_readlane_b32 s0, v254, 52
	v_or_b32_e32 v168, s41, v171
	v_mov_b32_e32 v137, v179
	v_mov_b32_e32 v139, v179
	s_mov_b32 s43, 0
	v_add_u32_e32 v145, 0, v18
	s_mov_b32 s82, s0
	v_mov_b32_e32 v3, v2
	v_mov_b32_e32 v4, v2
	v_mov_b32_e32 v5, v2
	v_mov_b32_e32 v6, v2
	v_mov_b32_e32 v7, v2
	v_mov_b32_e32 v8, v2
	v_mov_b32_e32 v9, v2
	v_mov_b32_e32 v18, v2
	v_mov_b32_e32 v19, v2
	v_mov_b32_e32 v20, v2
	v_mov_b32_e32 v21, v2
	v_mov_b32_e32 v22, v2
	v_mov_b32_e32 v23, v2
	v_mov_b32_e32 v24, v2
	v_mov_b32_e32 v25, v2
	v_mov_b32_e32 v34, v2
	v_mov_b32_e32 v35, v2
	v_mov_b32_e32 v36, v2
	v_mov_b32_e32 v37, v2
	v_mov_b32_e32 v38, v2
	v_mov_b32_e32 v39, v2
	v_mov_b32_e32 v40, v2
	v_mov_b32_e32 v41, v2
	v_mov_b32_e32 v50, v2
	v_mov_b32_e32 v51, v2
	v_mov_b32_e32 v52, v2
	v_mov_b32_e32 v53, v2
	v_mov_b32_e32 v54, v2
	v_mov_b32_e32 v55, v2
	v_mov_b32_e32 v56, v2
	v_mov_b32_e32 v57, v2
	v_mov_b32_e32 v10, v2
	v_mov_b32_e32 v11, v2
	v_mov_b32_e32 v12, v2
	v_mov_b32_e32 v13, v2
	v_mov_b32_e32 v14, v2
	v_mov_b32_e32 v15, v2
	v_mov_b32_e32 v16, v2
	v_mov_b32_e32 v17, v2
	v_mov_b32_e32 v26, v2
	v_mov_b32_e32 v27, v2
	v_mov_b32_e32 v28, v2
	v_mov_b32_e32 v29, v2
	v_mov_b32_e32 v30, v2
	v_mov_b32_e32 v31, v2
	v_mov_b32_e32 v32, v2
	v_mov_b32_e32 v33, v2
	v_mov_b32_e32 v42, v2
	v_mov_b32_e32 v43, v2
	v_mov_b32_e32 v44, v2
	v_mov_b32_e32 v45, v2
	v_mov_b32_e32 v46, v2
	v_mov_b32_e32 v47, v2
	v_mov_b32_e32 v48, v2
	v_mov_b32_e32 v49, v2
	v_mov_b32_e32 v58, v2
	v_mov_b32_e32 v59, v2
	v_mov_b32_e32 v60, v2
	v_mov_b32_e32 v61, v2
	v_mov_b32_e32 v62, v2
	v_mov_b32_e32 v63, v2
	v_mov_b32_e32 v64, v2
	v_mov_b32_e32 v65, v2
	v_mov_b32_e32 v66, v2
	v_mov_b32_e32 v67, v2
	v_mov_b32_e32 v68, v2
	v_mov_b32_e32 v69, v2
	v_mov_b32_e32 v70, v2
	v_mov_b32_e32 v71, v2
	v_mov_b32_e32 v72, v2
	v_mov_b32_e32 v73, v2
	v_mov_b32_e32 v82, v2
	v_mov_b32_e32 v83, v2
	v_mov_b32_e32 v84, v2
	v_mov_b32_e32 v85, v2
	v_mov_b32_e32 v86, v2
	v_mov_b32_e32 v87, v2
	v_mov_b32_e32 v88, v2
	v_mov_b32_e32 v89, v2
	v_mov_b32_e32 v98, v2
	v_mov_b32_e32 v99, v2
	v_mov_b32_e32 v100, v2
	v_mov_b32_e32 v101, v2
	v_mov_b32_e32 v102, v2
	v_mov_b32_e32 v103, v2
	v_mov_b32_e32 v104, v2
	v_mov_b32_e32 v105, v2
	v_mov_b32_e32 v114, v2
	v_mov_b32_e32 v115, v2
	v_mov_b32_e32 v116, v2
	v_mov_b32_e32 v117, v2
	v_mov_b32_e32 v118, v2
	v_mov_b32_e32 v119, v2
	v_mov_b32_e32 v120, v2
	v_mov_b32_e32 v121, v2
	v_mov_b32_e32 v74, v2
	v_mov_b32_e32 v75, v2
	v_mov_b32_e32 v76, v2
	v_mov_b32_e32 v77, v2
	v_mov_b32_e32 v78, v2
	v_mov_b32_e32 v79, v2
	v_mov_b32_e32 v80, v2
	v_mov_b32_e32 v81, v2
	v_mov_b32_e32 v90, v2
	v_mov_b32_e32 v91, v2
	v_mov_b32_e32 v92, v2
	v_mov_b32_e32 v93, v2
	v_mov_b32_e32 v94, v2
	v_mov_b32_e32 v95, v2
	v_mov_b32_e32 v96, v2
	v_mov_b32_e32 v97, v2
	v_mov_b32_e32 v106, v2
	v_mov_b32_e32 v107, v2
	v_mov_b32_e32 v108, v2
	v_mov_b32_e32 v109, v2
	v_mov_b32_e32 v110, v2
	v_mov_b32_e32 v111, v2
	v_mov_b32_e32 v112, v2
	v_mov_b32_e32 v113, v2
	v_mov_b32_e32 v122, v2
	v_mov_b32_e32 v123, v2
	v_mov_b32_e32 v124, v2
	v_mov_b32_e32 v125, v2
	v_mov_b32_e32 v126, v2
	v_mov_b32_e32 v127, v2
	v_mov_b32_e32 v128, v2
	v_mov_b32_e32 v129, v2
	s_barrier
	v_readlane_b32 s1, v254, 53

.LBB0_1011:
	v_lshl_add_u64 v[8:9], s[16:17], 0, v[178:179]
	v_mov_b32_e32 v131, v179
	v_and_b32_e32 v167, 15, v166
	v_and_b32_e32 v144, 48, v166
	v_lshlrev_b32_e32 v17, 2, v166
	v_lshl_add_u64 v[10:11], s[16:17], 0, v[130:131]
	v_mov_b32_e32 v135, v179
	s_and_b32 s1, s6, 3
	s_lshl_b32 s0, s12, 13
	v_lshl_or_b32 v16, v167, 6, v144
	v_and_b32_e32 v17, 32, v17
	s_add_i32 m0, s84, 0x18000
	v_lshl_add_u64 v[8:9], v[8:9], 0, s[90:91]
	v_lshl_add_u64 v[12:13], s[94:95], 0, v[134:135]
	v_mov_b32_e32 v133, v179
	s_lshl_b32 s96, s12, 6
	v_bitop3_b32 v19, v16, s0, v17 bitop3:0xde
	s_lshl_b32 s0, s1, 12
	s_waitcnt vmcnt(2)
	s_barrier
	global_load_lds_dwordx4 v[8:9], off
	v_lshl_add_u64 v[8:9], v[10:11], 0, s[90:91]
	s_add_i32 m0, s84, 0x1a000
	s_add_i32 s42, s84, 0x8000
	s_add_i32 s43, s84, 0xa000
	v_lshl_add_u64 v[14:15], s[94:95], 0, v[132:133]
	global_load_lds_dwordx4 v[8:9], off
	v_lshl_add_u64 v[8:9], v[12:13], 0, s[90:91]
	s_mov_b32 m0, s42
	s_add_u32 s4, s16, 0x40080
	global_load_lds_dwordx4 v[8:9], off
	v_lshl_add_u64 v[8:9], v[14:15], 0, s[90:91]
	s_mov_b32 m0, s43
	s_addc_u32 s5, s17, 0
	global_load_lds_dwordx4 v[8:9], off
	s_add_i32 m0, s84, 0x1c000
	v_lshl_add_u64 v[8:9], s[4:5], 0, v[178:179]
	global_load_lds_dwordx4 v[8:9], off
	v_lshl_add_u64 v[8:9], s[4:5], 0, v[130:131]
	s_add_i32 m0, s84, 0x1e000
	v_mov_b32_e32 v18, 0
	global_load_lds_dwordx4 v[8:9], off
	v_lshlrev_b32_e32 v8, 14, v6
	v_and_b32_e32 v8, 0xffff8000, v8
	v_lshl_add_u32 v5, v5, 11, v8
	v_and_b32_e32 v6, 1, v6
	v_lshl_or_b32 v5, v6, 6, v5
	v_lshl_add_u32 v136, v7, 1, v5
	v_lshlrev_b32_e32 v5, 14, v2
	v_and_b32_e32 v5, 0xffff8000, v5
	s_waitcnt vmcnt(6)
	v_lshl_add_u32 v3, v3, 11, v5
	v_and_b32_e32 v2, 1, v2
	v_lshl_or_b32 v2, v2, 6, v3
	v_readlane_b32 s4, v254, 52
	v_writelane_b32 v255, s6, 29
	v_or_b32_e32 v168, s96, v167
	v_bitop3_b32 v145, v16, s0, v17 bitop3:0xde
	v_mov_b32_e32 v137, v179
	v_lshl_add_u32 v138, v4, 1, v2
	v_mov_b32_e32 v139, v179
	s_mov_b32 s44, 0
	v_add_u32_e32 v146, 0, v19
	v_readlane_b32 s0, v254, 56
	s_mov_b32 s10, s4
	v_mov_b32_e32 v19, v18
	v_mov_b32_e32 v20, v18
	v_mov_b32_e32 v21, v18
	v_mov_b32_e32 v22, v18
	v_mov_b32_e32 v23, v18
	v_mov_b32_e32 v24, v18
	v_mov_b32_e32 v25, v18
	v_mov_b32_e32 v54, v18
	v_mov_b32_e32 v55, v18
	v_mov_b32_e32 v56, v18
	v_mov_b32_e32 v57, v18
	v_mov_b32_e32 v62, v18
	v_mov_b32_e32 v63, v18
	v_mov_b32_e32 v64, v18
	v_mov_b32_e32 v65, v18
	v_mov_b32_e32 v98, v18
	v_mov_b32_e32 v99, v18
	v_mov_b32_e32 v100, v18
	v_mov_b32_e32 v101, v18
	v_mov_b32_e32 v102, v18
	v_mov_b32_e32 v103, v18
	v_mov_b32_e32 v104, v18
	v_mov_b32_e32 v105, v18
	v_mov_b32_e32 v114, v18
	v_mov_b32_e32 v115, v18
	v_mov_b32_e32 v116, v18
	v_mov_b32_e32 v117, v18
	v_mov_b32_e32 v118, v18
	v_mov_b32_e32 v119, v18
	v_mov_b32_e32 v120, v18
	v_mov_b32_e32 v121, v18
	v_mov_b32_e32 v34, v18
	v_mov_b32_e32 v35, v18
	v_mov_b32_e32 v36, v18
	v_mov_b32_e32 v37, v18
	v_mov_b32_e32 v38, v18
	v_mov_b32_e32 v39, v18
	v_mov_b32_e32 v40, v18
	v_mov_b32_e32 v41, v18
	v_mov_b32_e32 v74, v18
	v_mov_b32_e32 v75, v18
	v_mov_b32_e32 v76, v18
	v_mov_b32_e32 v77, v18
	v_mov_b32_e32 v78, v18
	v_mov_b32_e32 v79, v18
	v_mov_b32_e32 v80, v18
	v_mov_b32_e32 v81, v18
	v_mov_b32_e32 v122, v18
	v_mov_b32_e32 v123, v18
	v_mov_b32_e32 v124, v18
	v_mov_b32_e32 v125, v18
	v_mov_b32_e32 v126, v18
	v_mov_b32_e32 v127, v18
	v_mov_b32_e32 v128, v18
	v_mov_b32_e32 v129, v18
	v_mov_b32_e32 v106, v18
	v_mov_b32_e32 v107, v18
	v_mov_b32_e32 v108, v18
	v_mov_b32_e32 v109, v18
	v_mov_b32_e32 v110, v18
	v_mov_b32_e32 v111, v18
	v_mov_b32_e32 v112, v18
	v_mov_b32_e32 v113, v18
	v_mov_b32_e32 v90, v18
	v_mov_b32_e32 v91, v18
	v_mov_b32_e32 v92, v18
	v_mov_b32_e32 v93, v18
	v_mov_b32_e32 v94, v18
	v_mov_b32_e32 v95, v18
	v_mov_b32_e32 v96, v18
	v_mov_b32_e32 v97, v18
	v_mov_b32_e32 v66, v18
	v_mov_b32_e32 v67, v18
	v_mov_b32_e32 v68, v18
	v_mov_b32_e32 v69, v18
	v_mov_b32_e32 v70, v18
	v_mov_b32_e32 v71, v18
	v_mov_b32_e32 v72, v18
	v_mov_b32_e32 v73, v18
	v_mov_b32_e32 v42, v18
	v_mov_b32_e32 v43, v18
	v_mov_b32_e32 v44, v18
	v_mov_b32_e32 v45, v18
	v_mov_b32_e32 v46, v18
	v_mov_b32_e32 v47, v18
	v_mov_b32_e32 v48, v18
	v_mov_b32_e32 v49, v18
	v_mov_b32_e32 v10, v18
	v_mov_b32_e32 v11, v18
	v_mov_b32_e32 v12, v18
	v_mov_b32_e32 v13, v18
	v_mov_b32_e32 v14, v18
	v_mov_b32_e32 v15, v18
	v_mov_b32_e32 v16, v18
	v_mov_b32_e32 v17, v18
	v_mov_b32_e32 v82, v18
	v_mov_b32_e32 v83, v18
	v_mov_b32_e32 v84, v18
	v_mov_b32_e32 v85, v18
	v_mov_b32_e32 v86, v18
	v_mov_b32_e32 v87, v18
	v_mov_b32_e32 v88, v18
	v_mov_b32_e32 v89, v18
	v_mov_b32_e32 v50, v18
	v_mov_b32_e32 v51, v18
	v_mov_b32_e32 v52, v18
	v_mov_b32_e32 v53, v18
	v_mov_b32_e32 v58, v18
	v_mov_b32_e32 v59, v18
	v_mov_b32_e32 v60, v18
	v_mov_b32_e32 v61, v18
	v_mov_b32_e32 v26, v18
	v_mov_b32_e32 v27, v18
	v_mov_b32_e32 v28, v18
	v_mov_b32_e32 v29, v18
	v_mov_b32_e32 v30, v18
	v_mov_b32_e32 v31, v18
	v_mov_b32_e32 v32, v18
	v_mov_b32_e32 v33, v18
	v_mov_b32_e32 v2, v18
	v_mov_b32_e32 v3, v18
	v_mov_b32_e32 v4, v18
	v_mov_b32_e32 v5, v18
	v_mov_b32_e32 v6, v18
	v_mov_b32_e32 v7, v18
	v_mov_b32_e32 v8, v18
	v_mov_b32_e32 v9, v18
	s_barrier
	v_readlane_b32 s5, v254, 53
.LBB0_1012:
	s_add_i32 s45, s44, 1
	s_mul_i32 s5, s45, s3
	s_mul_hi_i32 s4, s45, s3
	s_add_u32 s14, s5, s2
	s_addc_u32 s15, s4, s87
	v_cmp_gt_i64_e64 s[4:5], s[14:15], v[188:189]
	v_cmp_lt_i64_e64 s[6:7], s[14:15], v[186:187]
	s_and_b64 vcc, exec, s[4:5]
	s_cbranch_vccnz .LBB0_1018
	s_ashr_i32 s15, s14, 31
	s_lshr_b32 s15, s15, 29
	s_add_i32 s20, s14, s15
	s_and_b32 s15, s20, -8
	s_sub_i32 s21, s14, s15
	s_cmp_gt_i32 s21, -1
	s_mov_b64 s[14:15], -1
	s_cbranch_scc0 .LBB0_1015
	s_lshl_b32 s34, s21, 5
	s_mov_b64 s[14:15], 0

.LBB0_1122:
	s_add_u32 s4, s74, s4
	s_addc_u32 s5, s75, s5
	s_add_u32 s8, s4, 0xbc00000
	s_addc_u32 s9, s5, 0
	s_lshl_b32 s4, s18, 5
	s_and_b32 s22, s4, 0x60
	s_add_i32 m0, s21, 0x18000
	v_lshl_add_u64 v[8:9], v[8:9], 0, s[90:91]
	s_lshl_b32 s19, s17, 13
	s_lshl_b32 s18, s22, 7
	s_waitcnt vmcnt(2)
	s_barrier
	global_load_lds_dwordx4 v[8:9], off
	v_lshl_add_u64 v[6:7], v[6:7], 0, s[90:91]
	s_add_i32 m0, s21, 0x1a000
	s_add_i32 s61, s21, 0x8000
	s_add_i32 s82, s21, 0xa000
	global_load_lds_dwordx4 v[6:7], off
	v_lshl_add_u64 v[2:3], v[2:3], 0, s[90:91]
	s_mov_b32 m0, s61
	s_add_u32 s4, s14, 0x40080
	global_load_lds_dwordx4 v[2:3], off
	v_lshl_add_u64 v[2:3], v[4:5], 0, s[90:91]
	s_mov_b32 m0, s82
	s_addc_u32 s5, s15, 0
	global_load_lds_dwordx4 v[2:3], off
	s_add_i32 m0, s21, 0x1c000
	v_lshl_add_u64 v[2:3], s[4:5], 0, v[178:179]
	global_load_lds_dwordx4 v[2:3], off
	v_lshl_add_u64 v[2:3], s[4:5], 0, v[130:131]
	s_add_i32 m0, s21, 0x1e000
	s_cmpk_lt_u32 s16, 0x100
	global_load_lds_dwordx4 v[2:3], off
	v_lshrrev_b32_e32 v3, 1, v10
	v_and_b32_e32 v3, 24, v3
	v_and_b32_e32 v2, 15, v10
	v_lshlrev_b32_e32 v4, 1, v3
	v_lshl_or_b32 v142, s17, 6, v2
	v_lshl_or_b32 v2, v2, 6, v4
	v_lshlrev_b32_e32 v4, 2, v10
	v_and_b32_e32 v4, 32, v4
	v_bitop3_b32 v5, v2, s19, v4 bitop3:0xde
	v_bitop3_b32 v143, v2, s18, v4 bitop3:0xde
	v_lshlrev_b32_e32 v2, 14, v15
	v_and_b32_e32 v2, 0xffff8000, v2
	v_or_b32_e32 v144, s22, v3
	v_lshl_add_u32 v2, v14, 11, v2
	v_and_b32_e32 v3, 1, v15
	v_lshl_or_b32 v2, v3, 6, v2
	v_lshl_add_u32 v136, v16, 1, v2
	v_lshlrev_b32_e32 v2, 14, v11
	v_and_b32_e32 v2, 0xffff8000, v2
	s_waitcnt vmcnt(6)
	v_lshl_add_u32 v2, v12, 11, v2
	v_and_b32_e32 v3, 1, v11
	v_lshl_or_b32 v2, v3, 6, v2
	v_readlane_b32 s4, v254, 37
	s_cselect_b64 s[18:19], -1, 0
	v_mov_b32_e32 v137, v179
	v_lshl_add_u32 v138, v13, 1, v2
	v_mov_b32_e32 v139, v179
	s_mov_b32 s92, 0
	v_add_u32_e32 v145, 0, v5
	v_readlane_b32 s28, v254, 28
	s_mov_b32 s29, s4
	s_barrier
	v_readlane_b32 s5, v254, 38
	s_branch .LBB0_1125

.LBB0_1139:
	s_add_u32 s6, s74, s6
	s_addc_u32 s7, s75, s7
	s_add_u32 s6, s6, 0xf00000
	s_addc_u32 s7, s7, 0
	s_lshl_b32 s9, s9, 5
	s_and_b32 s22, s9, 0x60
	s_add_i32 m0, s13, 0x18000
	v_lshl_add_u64 v[8:9], v[8:9], 0, s[90:91]
	s_lshl_b32 s19, s8, 13
	s_lshl_b32 s9, s22, 7
	s_waitcnt vmcnt(2)
	s_barrier
	global_load_lds_dwordx4 v[8:9], off
	v_lshl_add_u64 v[6:7], v[6:7], 0, s[90:91]
	s_add_i32 m0, s13, 0x1a000
	s_add_i32 s40, s13, 0x8000
	s_add_i32 s41, s13, 0xa000
	global_load_lds_dwordx4 v[6:7], off
	v_lshl_add_u64 v[2:3], v[2:3], 0, s[90:91]
	s_mov_b32 m0, s40
	s_add_u32 s20, s14, 0x40080
	global_load_lds_dwordx4 v[2:3], off
	v_lshl_add_u64 v[2:3], v[4:5], 0, s[90:91]
	s_mov_b32 m0, s41
	s_addc_u32 s21, s15, 0
	global_load_lds_dwordx4 v[2:3], off
	s_add_i32 m0, s13, 0x1c000
	v_lshl_add_u64 v[2:3], s[20:21], 0, v[178:179]
	global_load_lds_dwordx4 v[2:3], off
	v_lshl_add_u64 v[2:3], s[20:21], 0, v[130:131]
	s_add_i32 m0, s13, 0x1e000
	s_cmpk_lt_u32 s18, 0x100
	global_load_lds_dwordx4 v[2:3], off
	v_lshrrev_b32_e32 v3, 1, v10
	v_and_b32_e32 v3, 24, v3
	v_and_b32_e32 v2, 15, v10
	v_lshlrev_b32_e32 v4, 1, v3
	v_lshl_or_b32 v142, s8, 6, v2
	v_lshl_or_b32 v2, v2, 6, v4
	v_lshlrev_b32_e32 v4, 2, v10
	v_and_b32_e32 v4, 32, v4
	v_bitop3_b32 v5, v2, s19, v4 bitop3:0xde
	v_bitop3_b32 v143, v2, s9, v4 bitop3:0xde
	v_lshlrev_b32_e32 v2, 14, v15
	v_and_b32_e32 v2, 0xffff8000, v2
	v_or_b32_e32 v144, s22, v3
	v_lshl_add_u32 v2, v14, 11, v2
	v_and_b32_e32 v3, 1, v15
	v_lshl_or_b32 v2, v3, 6, v2
	v_lshl_add_u32 v136, v16, 1, v2
	v_lshlrev_b32_e32 v2, 14, v11
	v_and_b32_e32 v2, 0xffff8000, v2
	s_waitcnt vmcnt(6)
	v_lshl_add_u32 v2, v12, 11, v2
	v_and_b32_e32 v3, 1, v11
	v_lshl_or_b32 v2, v3, 6, v2
	s_cselect_b64 s[8:9], -1, 0
	v_mov_b32_e32 v137, v179
	v_lshl_add_u32 v138, v13, 1, v2
	v_mov_b32_e32 v139, v179
	s_mov_b32 s42, 0
	v_add_u32_e32 v145, 0, v5
	v_readlane_b32 s43, v254, 12
	v_readlane_b32 s44, v254, 10
	s_barrier
	s_branch .LBB0_1142
